# context hyena Toeplitz MFMA section: fragment reads issued two block-shifts ahead in a register ring (same 44 reads, far fewer exposed waits)
# baseline (speedup 1.0000x reference)
.LBB0_499:
	s_or_b64 exec, exec, s[4:5]
	s_waitcnt lgkmcnt(0)
	s_barrier
	v_add_u32_e32 v75, v53, v55
	s_add_i32 s34, s25, s29
	s_xor_b64 s[4:5], s[0:1], -1
	s_lshl_b64 s[16:17], s[34:35], 2
	s_add_u32 s16, s90, s16
	s_addc_u32 s17, s91, s17
	s_and_b64 s[0:1], s[0:1], exec
	s_movk_i32 s0, 0x6900
	s_cselect_b32 s0, s0, 0xf100
	s_add_i32 s0, s0, 0
	s_and_b64 vcc, exec, s[4:5]
	ds_read_b128 v[152:155], v66 offset:8448
	ds_read_b128 v[156:159], v66 offset:8512
	ds_read_b128 v[76:79], v54 offset:960
	ds_read_b128 v[80:83], v54 offset:928
	ds_read_b128 v[84:87], v54 offset:896
	ds_read_b128 v[88:91], v54 offset:864
	ds_read_b128 v[96:99], v54 offset:832
	ds_read_b128 v[100:103], v54 offset:800
	ds_read_b128 v[160:163], v67 offset:8448
	ds_read_b128 v[164:167], v67 offset:8512
	ds_read_b128 v[104:107], v54 offset:768
	ds_read_b128 v[132:135], v54 offset:736
	ds_read_b128 v[136:139], v54 offset:704
	ds_read_b128 v[140:143], v54 offset:672
	s_waitcnt lgkmcnt(6)
	v_cndmask_b32_e64 v152, 0, v152, s[50:51]
	v_cndmask_b32_e64 v153, 0, v153, s[50:51]
	v_cndmask_b32_e64 v154, 0, v154, s[50:51]
	v_cndmask_b32_e64 v155, 0, v155, s[50:51]
	v_cndmask_b32_e64 v156, 0, v156, s[50:51]
	v_cndmask_b32_e64 v157, 0, v157, s[50:51]
	v_cndmask_b32_e64 v158, 0, v158, s[50:51]
	v_cndmask_b32_e64 v159, 0, v159, s[50:51]
	v_mfma_f32_16x16x32_bf16 v[92:95], v[84:87], v[152:155], 0
	v_mfma_f32_16x16x32_bf16 v[14:17], v[88:91], v[152:155], 0
	v_mfma_f32_16x16x32_bf16 v[10:13], v[96:99], v[152:155], 0
	v_mfma_f32_16x16x32_bf16 v[6:9], v[100:103], v[152:155], 0
	v_mfma_f32_16x16x32_bf16 v[92:95], v[76:79], v[156:159], v[92:95]
	v_mfma_f32_16x16x32_bf16 v[14:17], v[80:83], v[156:159], v[14:17]
	v_mfma_f32_16x16x32_bf16 v[10:13], v[84:87], v[156:159], v[10:13]
	v_mfma_f32_16x16x32_bf16 v[6:9], v[88:91], v[156:159], v[6:9]
	ds_read_b128 v[168:171], v68 offset:8448
	ds_read_b128 v[172:175], v68 offset:8512
	ds_read_b128 v[144:147], v54 offset:640
	ds_read_b128 v[148:151], v54 offset:608
	ds_read_b128 v[76:79], v54 offset:576
	ds_read_b128 v[80:83], v54 offset:544
	s_waitcnt lgkmcnt(6)
	v_cndmask_b32_e64 v160, 0, v160, s[52:53]
	v_cndmask_b32_e64 v161, 0, v161, s[52:53]
	v_cndmask_b32_e64 v162, 0, v162, s[52:53]
	v_cndmask_b32_e64 v163, 0, v163, s[52:53]
	v_cndmask_b32_e64 v164, 0, v164, s[52:53]
	v_cndmask_b32_e64 v165, 0, v165, s[52:53]
	v_cndmask_b32_e64 v166, 0, v166, s[52:53]
	v_cndmask_b32_e64 v167, 0, v167, s[52:53]
	v_mfma_f32_16x16x32_bf16 v[92:95], v[104:107], v[160:163], v[92:95]
	v_mfma_f32_16x16x32_bf16 v[14:17], v[132:135], v[160:163], v[14:17]
	v_mfma_f32_16x16x32_bf16 v[10:13], v[136:139], v[160:163], v[10:13]
	v_mfma_f32_16x16x32_bf16 v[6:9], v[140:143], v[160:163], v[6:9]
	v_mfma_f32_16x16x32_bf16 v[92:95], v[96:99], v[164:167], v[92:95]
	v_mfma_f32_16x16x32_bf16 v[14:17], v[100:103], v[164:167], v[14:17]
	v_mfma_f32_16x16x32_bf16 v[10:13], v[104:107], v[164:167], v[10:13]
	v_mfma_f32_16x16x32_bf16 v[6:9], v[132:135], v[164:167], v[6:9]
	ds_read_b128 v[152:155], v75 offset:8448
	ds_read_b128 v[156:159], v75 offset:8512
	ds_read_b128 v[84:87], v54 offset:512
	ds_read_b128 v[88:91], v54 offset:480
	ds_read_b128 v[96:99], v54 offset:448
	ds_read_b128 v[100:103], v54 offset:416
	s_waitcnt lgkmcnt(6)
	v_cndmask_b32_e64 v168, 0, v168, s[54:55]
	v_cndmask_b32_e64 v169, 0, v169, s[54:55]
	v_cndmask_b32_e64 v170, 0, v170, s[54:55]
	v_cndmask_b32_e64 v171, 0, v171, s[54:55]
	v_cndmask_b32_e64 v172, 0, v172, s[54:55]
	v_cndmask_b32_e64 v173, 0, v173, s[54:55]
	v_cndmask_b32_e64 v174, 0, v174, s[54:55]
	v_cndmask_b32_e64 v175, 0, v175, s[54:55]
	v_mfma_f32_16x16x32_bf16 v[92:95], v[144:147], v[168:171], v[92:95]
	v_mfma_f32_16x16x32_bf16 v[14:17], v[148:151], v[168:171], v[14:17]
	v_mfma_f32_16x16x32_bf16 v[10:13], v[76:79], v[168:171], v[10:13]
	v_mfma_f32_16x16x32_bf16 v[6:9], v[80:83], v[168:171], v[6:9]
	v_mfma_f32_16x16x32_bf16 v[92:95], v[136:139], v[172:175], v[92:95]
	v_mfma_f32_16x16x32_bf16 v[14:17], v[140:143], v[172:175], v[14:17]
	v_mfma_f32_16x16x32_bf16 v[10:13], v[144:147], v[172:175], v[10:13]
	v_mfma_f32_16x16x32_bf16 v[6:9], v[148:151], v[172:175], v[6:9]
	ds_read_b128 v[160:163], v69 offset:8448
	ds_read_b128 v[164:167], v69 offset:8512
	ds_read_b128 v[104:107], v54 offset:384
	ds_read_b128 v[132:135], v54 offset:352
	ds_read_b128 v[136:139], v54 offset:320
	ds_read_b128 v[140:143], v54 offset:288
	s_waitcnt lgkmcnt(6)
	v_mfma_f32_16x16x32_bf16 v[92:95], v[84:87], v[152:155], v[92:95]
	v_mfma_f32_16x16x32_bf16 v[14:17], v[88:91], v[152:155], v[14:17]
	v_mfma_f32_16x16x32_bf16 v[10:13], v[96:99], v[152:155], v[10:13]
	v_mfma_f32_16x16x32_bf16 v[6:9], v[100:103], v[152:155], v[6:9]
	v_mfma_f32_16x16x32_bf16 v[92:95], v[76:79], v[156:159], v[92:95]
	v_mfma_f32_16x16x32_bf16 v[14:17], v[80:83], v[156:159], v[14:17]
	v_mfma_f32_16x16x32_bf16 v[10:13], v[84:87], v[156:159], v[10:13]
	v_mfma_f32_16x16x32_bf16 v[6:9], v[88:91], v[156:159], v[6:9]
	ds_read_b128 v[168:171], v70 offset:8448
	ds_read_b128 v[172:175], v70 offset:8512
	ds_read_b128 v[144:147], v54 offset:256
	ds_read_b128 v[148:151], v54 offset:224
	ds_read_b128 v[76:79], v54 offset:192
	ds_read_b128 v[80:83], v54 offset:160
	s_waitcnt lgkmcnt(6)
	v_cndmask_b32_e64 v160, 0, v160, s[56:57]
	v_cndmask_b32_e64 v161, 0, v161, s[56:57]
	v_cndmask_b32_e64 v162, 0, v162, s[56:57]
	v_cndmask_b32_e64 v163, 0, v163, s[56:57]
	v_cndmask_b32_e64 v164, 0, v164, s[56:57]
	v_cndmask_b32_e64 v165, 0, v165, s[56:57]
	v_cndmask_b32_e64 v166, 0, v166, s[56:57]
	v_cndmask_b32_e64 v167, 0, v167, s[56:57]
	v_mfma_f32_16x16x32_bf16 v[92:95], v[104:107], v[160:163], v[92:95]
	v_mfma_f32_16x16x32_bf16 v[14:17], v[132:135], v[160:163], v[14:17]
	v_mfma_f32_16x16x32_bf16 v[10:13], v[136:139], v[160:163], v[10:13]
	v_mfma_f32_16x16x32_bf16 v[6:9], v[140:143], v[160:163], v[6:9]
	v_mfma_f32_16x16x32_bf16 v[92:95], v[96:99], v[164:167], v[92:95]
	v_mfma_f32_16x16x32_bf16 v[14:17], v[100:103], v[164:167], v[14:17]
	v_mfma_f32_16x16x32_bf16 v[10:13], v[104:107], v[164:167], v[10:13]
	v_mfma_f32_16x16x32_bf16 v[6:9], v[132:135], v[164:167], v[6:9]
	ds_read_b128 v[152:155], v71 offset:8448
	ds_read_b128 v[156:159], v71 offset:8512
	ds_read_b128 v[84:87], v54 offset:128
	ds_read_b128 v[88:91], v54 offset:96
	ds_read_b128 v[96:99], v54 offset:64
	ds_read_b128 v[100:103], v54 offset:32
	s_waitcnt lgkmcnt(6)
	v_cndmask_b32_e64 v168, 0, v168, s[58:59]
	v_cndmask_b32_e64 v169, 0, v169, s[58:59]
	v_cndmask_b32_e64 v170, 0, v170, s[58:59]
	v_cndmask_b32_e64 v171, 0, v171, s[58:59]
	v_cndmask_b32_e64 v172, 0, v172, s[58:59]
	v_cndmask_b32_e64 v173, 0, v173, s[58:59]
	v_cndmask_b32_e64 v174, 0, v174, s[58:59]
	v_cndmask_b32_e64 v175, 0, v175, s[58:59]
	v_mfma_f32_16x16x32_bf16 v[92:95], v[144:147], v[168:171], v[92:95]
	v_mfma_f32_16x16x32_bf16 v[14:17], v[148:151], v[168:171], v[14:17]
	v_mfma_f32_16x16x32_bf16 v[10:13], v[76:79], v[168:171], v[10:13]
	v_mfma_f32_16x16x32_bf16 v[6:9], v[80:83], v[168:171], v[6:9]
	v_mfma_f32_16x16x32_bf16 v[92:95], v[136:139], v[172:175], v[92:95]
	v_mfma_f32_16x16x32_bf16 v[14:17], v[140:143], v[172:175], v[14:17]
	v_mfma_f32_16x16x32_bf16 v[10:13], v[144:147], v[172:175], v[10:13]
	v_mfma_f32_16x16x32_bf16 v[6:9], v[148:151], v[172:175], v[6:9]
	s_waitcnt lgkmcnt(0)
	s_barrier
	global_load_dword v75, v0, s[16:17]
	v_cndmask_b32_e64 v152, 0, v152, s[60:61]
	v_cndmask_b32_e64 v153, 0, v153, s[60:61]
	v_cndmask_b32_e64 v154, 0, v154, s[60:61]
	v_cndmask_b32_e64 v155, 0, v155, s[60:61]
	v_cndmask_b32_e64 v156, 0, v156, s[60:61]
	v_cndmask_b32_e64 v157, 0, v157, s[60:61]
	v_cndmask_b32_e64 v158, 0, v158, s[60:61]
	v_cndmask_b32_e64 v159, 0, v159, s[60:61]
	v_mfma_f32_16x16x32_bf16 v[92:95], v[84:87], v[152:155], v[92:95]
	v_mfma_f32_16x16x32_bf16 v[14:17], v[88:91], v[152:155], v[14:17]
	v_mfma_f32_16x16x32_bf16 v[10:13], v[96:99], v[152:155], v[10:13]
	v_mfma_f32_16x16x32_bf16 v[6:9], v[100:103], v[152:155], v[6:9]
	v_mfma_f32_16x16x32_bf16 v[92:95], v[76:79], v[156:159], v[92:95]
	v_mfma_f32_16x16x32_bf16 v[14:17], v[80:83], v[156:159], v[14:17]
	v_mfma_f32_16x16x32_bf16 v[10:13], v[84:87], v[156:159], v[10:13]
	v_mfma_f32_16x16x32_bf16 v[6:9], v[88:91], v[156:159], v[6:9]
	ds_read_b64 v[76:77], v59 offset:8448
	s_waitcnt lgkmcnt(0)
	v_lshlrev_b32_e32 v82, 16, v76
	v_and_b32_e32 v83, 0xffff0000, v76
	v_lshlrev_b32_e32 v76, 2, v18
	v_add3_u32 v76, s0, v56, v76
	ds_read_b128 v[78:81], v76
	v_lshlrev_b32_e32 v84, 16, v77
	v_and_b32_e32 v85, 0xffff0000, v77
	s_mov_b64 s[0:1], -1
	s_waitcnt vmcnt(0)
	v_fma_f32 v77, v75, v82, v92
	s_waitcnt lgkmcnt(0)
	v_mul_f32_e32 v77, v78, v77
	v_fma_f32 v78, v75, v83, v93
	v_mul_f32_e32 v78, v79, v78
	v_fma_f32 v79, v75, v84, v94
	v_fmac_f32_e32 v95, v75, v85
	v_mul_f32_e32 v79, v80, v79
	v_mul_f32_e32 v80, v81, v95
	s_cbranch_vccz .LBB0_501
	v_mul_f32_e32 v81, v35, v77
	v_bfe_u32 v82, v81, 16, 1
	v_add3_u32 v81, v81, v82, s18
	v_add_u32_e32 v82, s24, v60
	ds_write_b16_d16_hi v82, v81
	v_mul_f32_e32 v81, v37, v78
	v_bfe_u32 v83, v81, 16, 1
	v_add3_u32 v81, v81, v83, s18
	ds_write_b16_d16_hi v82, v81 offset:4
	v_mul_f32_e32 v81, v40, v79
	v_bfe_u32 v83, v81, 16, 1
	v_add3_u32 v81, v81, v83, s18
	ds_write_b16_d16_hi v82, v81 offset:8
	v_mul_f32_e32 v81, v41, v80
	v_bfe_u32 v83, v81, 16, 1
	v_add3_u32 v81, v81, v83, s18
	ds_write_b16_d16_hi v82, v81 offset:12
	s_mov_b64 s[0:1], 0
